# loop-edge: attention tile-loop back edge rotated (bookkeeping + exit/inactive tests before the barrier on the active path), on top of best
# speedup vs baseline: 1.0073x; 1.0073x over previous
; #define GLOAD(t_, slotoff_) do { const char* kb_ = KGc + ((size_t)(t_) << 14); const char* vb_ = VGc + ((size_t)(t_) << 14); \
;         const unsigned d_ = (unsigned)__builtin_amdgcn_readfirstlane((int)(ldsbase + (slotoff_) + wid * 1024)); \
;         GLDS16(kb_, d_); GLDS16(kb_ + 8192, d_ + 8192u); GLDS16(vb_, d_ + 16384u); GLDS16(vb_ + 8192, d_ + 24576u); } while (0)
; #define SCHEDB() __builtin_amdgcn_sched_barrier(0)
; #define LOADV(dst, ks_) do { _Pragma("unroll") for (int dvb = 0; dvb < 4; ++dvb) { dst[2 * dvb] = vtr(vp + dvb * 4096 + (ks_) * 1024); dst[2 * dvb + 1] = vtr(vp + dvb * 4096 + (ks_) * 1024 + 512); } } while (0)
; #define MF4(src, pfrag) do { _Pragma("unroll") for (int dvb = 0; dvb < 4; ++dvb) { \
;         const bf16x8 vf_ = __builtin_shufflevector(src[2 * dvb], src[2 * dvb + 1], 0, 1, 2, 3, 4, 5, 6, 7); o[dvb] = MFMA32(vf_, pfrag, o[dvb]); } } while (0)
; #define EXPQ(S, lo_, RS, PF) do { _Pragma("unroll") for (int i = lo_; i < lo_ + 8; ++i) { S[i] = ex2(S[i]); RS += S[i]; } \
;               u32x4 w_; w_.x = pk2(S[lo_], S[lo_ + 1]); w_.y = pk2(S[lo_ + 2], S[lo_ + 3]); w_.z = pk2(S[lo_ + 4], S[lo_ + 5]); w_.w = pk2(S[lo_ + 6], S[lo_ + 7]); PF = __builtin_bit_cast(bf16x8, w_); } while (0)
; DI void attn_unit(const Params& p, int bh, int qb, char* lds, float lam, int tid, int lane, int wid, const bool build_tab) {
;     ...
;             float rs0 = 0.f, rs1 = 0.f;
;     ...
;             EXPQ(s0, 0, rs0, pf[0]);
;             LOADV(vb, 1);
;             MF4(va, pf[0]);
;             EXPQ(s0, 8, rs1, pf[1]);
;             LOADV(va, 2);
;             MF4(vb, pf[1]);
;             EXPQ(s1, 0, rs0, pf[2]);
;             LOADV(vb, 3);
;             MF4(va, pf[2]);
;             EXPQ(s1, 8, rs1, pf[3]);
;             MF4(vb, pf[3]);
;             l += rs0 + rs1;
;     ...
;         } else {
;             asm volatile("s_waitcnt vmcnt(0)" ::: "memory");
;             if (t + 2 < NT) GLOAD(t + 2, sn2);
;         }
;         SCHEDB();
;         __builtin_amdgcn_s_barrier();
;         SCHEDB();
;         { const int tmp = sc; sc = sn1; sn1 = sn2; sn2 = tmp; }
;     }
.LBB0_359:
	ds_read_b64_tr_b16 v[242:243], v220 offset:21504
	ds_read_b64_tr_b16 v[244:245], v220 offset:22016
	ds_read_b64_tr_b16 v[246:247], v220 offset:25600
	ds_read_b64_tr_b16 v[248:249], v220 offset:26112
	v_exp_f32_e32 v222, v96
	v_exp_f32_e32 v224, v97
	v_exp_f32_e32 v226, v98
	v_exp_f32_e32 v228, v99
	v_exp_f32_e32 v230, v100
	v_exp_f32_e32 v232, v101
	v_exp_f32_e32 v234, v102
	v_exp_f32_e32 v236, v103
	v_cvt_pk_bf16_f32 v96, v222, v224
	v_cvt_pk_bf16_f32 v97, v226, v228
	v_cvt_pk_bf16_f32 v98, v230, v232
	v_cvt_pk_bf16_f32 v99, v234, v236
	ds_read_b64_tr_b16 v[100:101], v220 offset:17408
	ds_read_b64_tr_b16 v[102:103], v220 offset:17920
	s_waitcnt lgkmcnt(12)
	v_mfma_f32_32x32x16_bf16 v[48:63], v[140:143], v[96:99], v[48:63]
	ds_read_b64_tr_b16 v[250:251], v220 offset:29696
	ds_read_b64_tr_b16 v[252:253], v220 offset:30208
	v_exp_f32_e32 v223, v104
	v_exp_f32_e32 v225, v105
	v_exp_f32_e32 v227, v106
	v_add_f32_e32 v221, v224, v222
	s_waitcnt lgkmcnt(12)
	v_mfma_f32_32x32x16_bf16 v[32:47], v[136:139], v[96:99], v[32:47]
	v_exp_f32_e32 v229, v107
	v_exp_f32_e32 v231, v108
	v_exp_f32_e32 v233, v109
	v_add_f32_e32 v221, v226, v221
	s_waitcnt lgkmcnt(10)
	v_mfma_f32_32x32x16_bf16 v[16:31], v[132:135], v[96:99], v[16:31]
	v_exp_f32_e32 v235, v110
	v_exp_f32_e32 v237, v111
	v_add_f32_e32 v221, v228, v221
	v_add_f32_e32 v221, v230, v221
	ds_read_b64_tr_b16 v[104:105], v220 offset:18432
	ds_read_b64_tr_b16 v[106:107], v220 offset:18944
	ds_read_b64_tr_b16 v[108:109], v220 offset:19456
	ds_read_b64_tr_b16 v[110:111], v220 offset:19968
	s_waitcnt lgkmcnt(12)
	v_mfma_f32_32x32x16_bf16 v[0:15], v[128:131], v[96:99], v[0:15]
	ds_read_b64_tr_b16 v[128:129], v220 offset:26624
	ds_read_b64_tr_b16 v[130:131], v220 offset:27136
	v_cvt_pk_bf16_f32 v96, v223, v225
	v_cvt_pk_bf16_f32 v97, v227, v229
	v_cvt_pk_bf16_f32 v98, v231, v233
	v_cvt_pk_bf16_f32 v99, v235, v237
	v_exp_f32_e32 v140, v84
	v_exp_f32_e32 v142, v85
	s_waitcnt lgkmcnt(8)
	v_mfma_f32_32x32x16_bf16 v[48:63], v[100:103], v[96:99], v[48:63]
	v_exp_f32_e32 v238, v86
	v_exp_f32_e32 v240, v87
	v_add_f32_e32 v221, v232, v221
	ds_read_b64_tr_b16 v[84:85], v220 offset:22528
	ds_read_b64_tr_b16 v[86:87], v220 offset:23040
	v_exp_f32_e32 v136, v82
	s_waitcnt lgkmcnt(14)
	v_mfma_f32_32x32x16_bf16 v[32:47], v[242:245], v[96:99], v[32:47]
	ds_read_b64_tr_b16 v[242:243], v220 offset:23552
	ds_read_b64_tr_b16 v[244:245], v220 offset:24064
	v_exp_f32_e32 v138, v83
	v_exp_f32_e32 v132, v80
	v_exp_f32_e32 v134, v81
	v_add_f32_e32 v221, v234, v221
	s_waitcnt lgkmcnt(14)
	v_mfma_f32_32x32x16_bf16 v[16:31], v[246:249], v[96:99], v[16:31]
	ds_read_b64_tr_b16 v[246:247], v220 offset:27648
	ds_read_b64_tr_b16 v[248:249], v220 offset:28160
	v_cvt_pk_bf16_f32 v80, v132, v134
	v_cvt_pk_bf16_f32 v81, v136, v138
	v_cvt_pk_bf16_f32 v82, v140, v142
	v_cvt_pk_bf16_f32 v83, v238, v240
	v_exp_f32_e32 v133, v88
	v_exp_f32_e32 v135, v89
	s_waitcnt lgkmcnt(12)
	v_mfma_f32_32x32x16_bf16 v[0:15], v[250:253], v[96:99], v[0:15]
	ds_read_b64_tr_b16 v[250:251], v220 offset:31744
	ds_read_b64_tr_b16 v[252:253], v220 offset:32256
	v_exp_f32_e32 v137, v90
	v_exp_f32_e32 v139, v91
	v_add_f32_e32 v221, v236, v221
	ds_read_b64_tr_b16 v[88:89], v220 offset:30720
	ds_read_b64_tr_b16 v[90:91], v220 offset:31232
	v_exp_f32_e32 v141, v92
	s_waitcnt lgkmcnt(14)
	v_mfma_f32_32x32x16_bf16 v[48:63], v[104:107], v[80:83], v[48:63]
	v_exp_f32_e32 v143, v93
	v_exp_f32_e32 v239, v94
	v_exp_f32_e32 v241, v95
	v_add_f32_e32 v221, v132, v221
	s_waitcnt lgkmcnt(8)
	v_mfma_f32_32x32x16_bf16 v[32:47], v[84:87], v[80:83], v[32:47]
	v_add_f32_e32 v93, v225, v223
	v_add_f32_e32 v221, v134, v221
	v_add_f32_e32 v93, v227, v93
	v_add_f32_e32 v221, v136, v221
	v_add_f32_e32 v93, v229, v93
	v_add_f32_e32 v221, v138, v221
	s_waitcnt lgkmcnt(10)
	v_mfma_f32_32x32x16_bf16 v[16:31], v[128:131], v[80:83], v[16:31]
	v_add_f32_e32 v93, v231, v93
	v_add_f32_e32 v221, v140, v221
	v_add_f32_e32 v93, v233, v93
	v_add_f32_e32 v221, v142, v221
	v_add_f32_e32 v93, v235, v93
	v_add_f32_e32 v221, v238, v221
	v_add_f32_e32 v93, v237, v93
	s_waitcnt lgkmcnt(0)
	v_mfma_f32_32x32x16_bf16 v[0:15], v[88:91], v[80:83], v[0:15]
	v_cvt_pk_bf16_f32 v80, v133, v135
	v_cvt_pk_bf16_f32 v81, v137, v139
	v_cvt_pk_bf16_f32 v82, v141, v143
	v_cvt_pk_bf16_f32 v83, v239, v241
	v_add_f32_e32 v221, v240, v221
	v_add_f32_e32 v93, v133, v93
	s_waitcnt lgkmcnt(12)
	v_mfma_f32_32x32x16_bf16 v[48:63], v[108:111], v[80:83], v[48:63]
	v_add_f32_e32 v93, v135, v93
	v_add_f32_e32 v93, v137, v93
	s_waitcnt lgkmcnt(6)
	v_mfma_f32_32x32x16_bf16 v[32:47], v[242:245], v[80:83], v[32:47]
	v_add_f32_e32 v93, v139, v93
	v_add_f32_e32 v93, v141, v93
	s_waitcnt lgkmcnt(4)
	v_mfma_f32_32x32x16_bf16 v[16:31], v[246:249], v[80:83], v[16:31]
	v_add_f32_e32 v93, v143, v93
	v_add_f32_e32 v93, v239, v93
	s_waitcnt lgkmcnt(2)
	v_mfma_f32_32x32x16_bf16 v[0:15], v[250:253], v[80:83], v[0:15]
	v_add_f32_e32 v93, v241, v93
	v_add_f32_e32 v221, v221, v93
	v_add_f32_e32 v146, v146, v221
	s_add_i32 s7, s7, 1
	s_addk_i32 s83, 0x100
	v_lshl_add_u64 v[200:201], v[200:201], 0, s[18:19]
	s_cmp_eq_u32 s81, s83
	s_cbranch_scc1 .Lrot_exit_u1
	s_mov_b32 s50, s80
	s_mov_b32 s80, s82
	s_mov_b32 s82, s84
	s_mov_b32 s84, s50
	s_cmp_ge_u32 s7, s78
	s_cbranch_scc1 .Lrot_na_u1
	s_barrier
	s_branch .Lrot_s1_u1
.Lrot_exit_u1:
	s_barrier
	s_branch .LBB0_362

; #define GLOAD(t_, slotoff_) do { const char* kb_ = KGc + ((size_t)(t_) << 14); const char* vb_ = VGc + ((size_t)(t_) << 14); \
;         const unsigned d_ = (unsigned)__builtin_amdgcn_readfirstlane((int)(ldsbase + (slotoff_) + wid * 1024)); \
;         GLDS16(kb_, d_); GLDS16(kb_ + 8192, d_ + 8192u); GLDS16(vb_, d_ + 16384u); GLDS16(vb_ + 8192, d_ + 24576u); } while (0)
; #define SCHEDB() __builtin_amdgcn_sched_barrier(0)
; #define LOADV(dst, ks_) do { _Pragma("unroll") for (int dvb = 0; dvb < 4; ++dvb) { dst[2 * dvb] = vtr(vp + dvb * 4096 + (ks_) * 1024); dst[2 * dvb + 1] = vtr(vp + dvb * 4096 + (ks_) * 1024 + 512); } } while (0)
; #define MF4(src, pfrag) do { _Pragma("unroll") for (int dvb = 0; dvb < 4; ++dvb) { \
;         const bf16x8 vf_ = __builtin_shufflevector(src[2 * dvb], src[2 * dvb + 1], 0, 1, 2, 3, 4, 5, 6, 7); o[dvb] = MFMA32(vf_, pfrag, o[dvb]); } } while (0)
; #define EXPQ(S, lo_, RS, PF) do { _Pragma("unroll") for (int i = lo_; i < lo_ + 8; ++i) { S[i] = ex2(S[i]); RS += S[i]; } \
;               u32x4 w_; w_.x = pk2(S[lo_], S[lo_ + 1]); w_.y = pk2(S[lo_ + 2], S[lo_ + 3]); w_.z = pk2(S[lo_ + 4], S[lo_ + 5]); w_.w = pk2(S[lo_ + 6], S[lo_ + 7]); PF = __builtin_bit_cast(bf16x8, w_); } while (0)
; DI void attn_unit(const Params& p, int bh, int qb, char* lds, float lam, int tid, int lane, int wid, const bool build_tab) {
;     ...
;             float rs0 = 0.f, rs1 = 0.f;
;     ...
;             EXPQ(s0, 0, rs0, pf[0]);
;             LOADV(vb, 1);
;             MF4(va, pf[0]);
;             EXPQ(s0, 8, rs1, pf[1]);
;             LOADV(va, 2);
;             MF4(vb, pf[1]);
;             EXPQ(s1, 0, rs0, pf[2]);
;             LOADV(vb, 3);
;             MF4(va, pf[2]);
;             EXPQ(s1, 8, rs1, pf[3]);
;             MF4(vb, pf[3]);
;             l += rs0 + rs1;
;     ...
;         } else {
;             asm volatile("s_waitcnt vmcnt(0)" ::: "memory");
;             if (t + 2 < NT) GLOAD(t + 2, sn2);
;         }
;         SCHEDB();
;         __builtin_amdgcn_s_barrier();
;         SCHEDB();
;         { const int tmp = sc; sc = sn1; sn1 = sn2; sn2 = tmp; }
.LBB0_379:
	ds_read_b64_tr_b16 v[230:231], v177 offset:21504
	ds_read_b64_tr_b16 v[232:233], v177 offset:22016
	ds_read_b64_tr_b16 v[234:235], v177 offset:25600
	ds_read_b64_tr_b16 v[236:237], v177 offset:26112
	v_exp_f32_e32 v178, v96
	v_exp_f32_e32 v180, v97
	v_exp_f32_e32 v182, v98
	v_exp_f32_e32 v184, v99
	v_exp_f32_e32 v186, v100
	v_exp_f32_e32 v188, v101
	v_exp_f32_e32 v190, v102
	v_exp_f32_e32 v192, v103
	v_cvt_pk_bf16_f32 v96, v178, v180
	v_cvt_pk_bf16_f32 v97, v182, v184
	v_cvt_pk_bf16_f32 v98, v186, v188
	v_cvt_pk_bf16_f32 v99, v190, v192
	ds_read_b64_tr_b16 v[100:101], v177 offset:17408
	ds_read_b64_tr_b16 v[102:103], v177 offset:17920
	s_waitcnt lgkmcnt(12)
	v_mfma_f32_32x32x16_bf16 v[48:63], v[140:143], v[96:99], v[48:63]
	ds_read_b64_tr_b16 v[238:239], v177 offset:29696
	ds_read_b64_tr_b16 v[240:241], v177 offset:30208
	v_exp_f32_e32 v179, v104
	v_exp_f32_e32 v181, v105
	v_exp_f32_e32 v183, v106
	v_add_f32_e32 v242, v180, v178
	s_waitcnt lgkmcnt(12)
	v_mfma_f32_32x32x16_bf16 v[32:47], v[136:139], v[96:99], v[32:47]
	v_exp_f32_e32 v185, v107
	v_exp_f32_e32 v187, v108
	v_exp_f32_e32 v189, v109
	v_add_f32_e32 v242, v182, v242
	s_waitcnt lgkmcnt(10)
	v_mfma_f32_32x32x16_bf16 v[16:31], v[132:135], v[96:99], v[16:31]
	v_exp_f32_e32 v191, v110
	v_exp_f32_e32 v193, v111
	v_add_f32_e32 v242, v184, v242
	v_add_f32_e32 v242, v186, v242
	ds_read_b64_tr_b16 v[104:105], v177 offset:18432
	ds_read_b64_tr_b16 v[106:107], v177 offset:18944
	ds_read_b64_tr_b16 v[108:109], v177 offset:19456
	ds_read_b64_tr_b16 v[110:111], v177 offset:19968
	s_waitcnt lgkmcnt(12)
	v_mfma_f32_32x32x16_bf16 v[0:15], v[128:131], v[96:99], v[0:15]
	ds_read_b64_tr_b16 v[128:129], v177 offset:26624
	ds_read_b64_tr_b16 v[130:131], v177 offset:27136
	v_cvt_pk_bf16_f32 v96, v179, v181
	v_cvt_pk_bf16_f32 v97, v183, v185
	v_cvt_pk_bf16_f32 v98, v187, v189
	v_cvt_pk_bf16_f32 v99, v191, v193
	v_exp_f32_e32 v140, v84
	v_exp_f32_e32 v142, v85
	s_waitcnt lgkmcnt(8)
	v_mfma_f32_32x32x16_bf16 v[48:63], v[100:103], v[96:99], v[48:63]
	v_exp_f32_e32 v194, v86
	v_exp_f32_e32 v196, v87
	v_add_f32_e32 v242, v188, v242
	ds_read_b64_tr_b16 v[84:85], v177 offset:22528
	ds_read_b64_tr_b16 v[86:87], v177 offset:23040
	v_exp_f32_e32 v136, v82
	s_waitcnt lgkmcnt(14)
	v_mfma_f32_32x32x16_bf16 v[32:47], v[230:233], v[96:99], v[32:47]
	ds_read_b64_tr_b16 v[230:231], v177 offset:23552
	ds_read_b64_tr_b16 v[232:233], v177 offset:24064
	v_exp_f32_e32 v138, v83
	v_exp_f32_e32 v132, v80
	v_exp_f32_e32 v134, v81
	v_add_f32_e32 v242, v190, v242
	s_waitcnt lgkmcnt(14)
	v_mfma_f32_32x32x16_bf16 v[16:31], v[234:237], v[96:99], v[16:31]
	ds_read_b64_tr_b16 v[234:235], v177 offset:27648
	ds_read_b64_tr_b16 v[236:237], v177 offset:28160
	v_cvt_pk_bf16_f32 v80, v132, v134
	v_cvt_pk_bf16_f32 v81, v136, v138
	v_cvt_pk_bf16_f32 v82, v140, v142
	v_cvt_pk_bf16_f32 v83, v194, v196
	v_exp_f32_e32 v133, v88
	v_exp_f32_e32 v135, v89
	s_waitcnt lgkmcnt(12)
	v_mfma_f32_32x32x16_bf16 v[0:15], v[238:241], v[96:99], v[0:15]
	ds_read_b64_tr_b16 v[238:239], v177 offset:31744
	ds_read_b64_tr_b16 v[240:241], v177 offset:32256
	v_exp_f32_e32 v137, v90
	v_exp_f32_e32 v139, v91
	v_add_f32_e32 v242, v192, v242
	ds_read_b64_tr_b16 v[88:89], v177 offset:30720
	ds_read_b64_tr_b16 v[90:91], v177 offset:31232
	v_exp_f32_e32 v141, v92
	s_waitcnt lgkmcnt(14)
	v_mfma_f32_32x32x16_bf16 v[48:63], v[104:107], v[80:83], v[48:63]
	v_exp_f32_e32 v143, v93
	v_exp_f32_e32 v195, v94
	v_exp_f32_e32 v197, v95
	v_add_f32_e32 v242, v132, v242
	s_waitcnt lgkmcnt(8)
	v_mfma_f32_32x32x16_bf16 v[32:47], v[84:87], v[80:83], v[32:47]
	v_add_f32_e32 v243, v181, v179
	v_add_f32_e32 v242, v134, v242
	v_add_f32_e32 v243, v183, v243
	v_add_f32_e32 v242, v136, v242
	v_add_f32_e32 v243, v185, v243
	v_add_f32_e32 v242, v138, v242
	s_waitcnt lgkmcnt(10)
	v_mfma_f32_32x32x16_bf16 v[16:31], v[128:131], v[80:83], v[16:31]
	v_add_f32_e32 v243, v187, v243
	v_add_f32_e32 v242, v140, v242
	v_add_f32_e32 v243, v189, v243
	v_add_f32_e32 v242, v142, v242
	v_add_f32_e32 v243, v191, v243
	v_add_f32_e32 v242, v194, v242
	v_add_f32_e32 v243, v193, v243
	s_waitcnt lgkmcnt(0)
	v_mfma_f32_32x32x16_bf16 v[0:15], v[88:91], v[80:83], v[0:15]
	v_cvt_pk_bf16_f32 v80, v133, v135
	v_cvt_pk_bf16_f32 v81, v137, v139
	v_cvt_pk_bf16_f32 v82, v141, v143
	v_cvt_pk_bf16_f32 v83, v195, v197
	v_add_f32_e32 v242, v196, v242
	v_add_f32_e32 v243, v133, v243
	s_waitcnt lgkmcnt(12)
	v_mfma_f32_32x32x16_bf16 v[48:63], v[108:111], v[80:83], v[48:63]
	v_add_f32_e32 v243, v135, v243
	v_add_f32_e32 v243, v137, v243
	s_waitcnt lgkmcnt(6)
	v_mfma_f32_32x32x16_bf16 v[32:47], v[230:233], v[80:83], v[32:47]
	v_add_f32_e32 v243, v139, v243
	v_add_f32_e32 v243, v141, v243
	s_waitcnt lgkmcnt(4)
	v_mfma_f32_32x32x16_bf16 v[16:31], v[234:237], v[80:83], v[16:31]
	v_add_f32_e32 v243, v143, v243
	v_add_f32_e32 v243, v195, v243
	s_waitcnt lgkmcnt(2)
	v_mfma_f32_32x32x16_bf16 v[0:15], v[238:241], v[80:83], v[0:15]
	v_add_f32_e32 v243, v197, v243
	v_add_f32_e32 v242, v242, v243
	v_add_f32_e32 v176, v176, v242
	s_add_i32 s51, s51, 1
	s_addk_i32 s69, 0x100
	v_lshl_add_u64 v[174:175], v[174:175], 0, s[18:19]
	s_cmp_eq_u32 s54, s69
	s_cbranch_scc1 .Lrot_exit_u2
	s_mov_b32 s52, s68
	s_mov_b32 s68, s67
	s_mov_b32 s67, s70
	s_mov_b32 s70, s52
	s_cmp_ge_u32 s51, s56
	s_cbranch_scc1 .Lrot_na_u2
	s_barrier
	s_branch .Lrot_s1_u2
